# speedup vs baseline: 1.0040x; 1.0040x over previous
; #define LAS __attribute__((address_space(3)))
; __device__ __forceinline__ void transpose_item(const float* W, int N, bf16* WT, int ldk, int k0, int n0, int row_base, LAS float* scr, int lane) {
; #pragma unroll
;     for (int i = 0; i < 32; ++i) { const int kk = 2 * i + (lane >> 5); scr[kk * 33 + (lane & 31)] = W[(size_t)(k0 + kk) * N + n0 + (lane & 31)]; }
; __global__ void __launch_bounds__(NTHREADS, 2) fwd_kernel(Args args) {
;     ...
;             for (int q = 0; q < 2; ++q) { const int it = (int)it0 + q; if (it >= I_ALL) break;
;                 if (it < I_D) { const int kb = it / (DM / 32), nb_ = it % (DM / 32); transpose_item(ap->in[I_W1D], DM, WD, FF, 64 * kb, 32 * nb_, 32 * nb_, scr, lane); }
;                 else if (it < I_D + I_IN) { const int r = it - I_D, kb = r / (PROJ / 32), nb_ = r % (PROJ / 32); transpose_item(ap->in[I_WIN], PROJ, WIN, DM, 64 * kb, 32 * nb_, 32 * nb_, scr, lane); }
;                 else { const int r = it - I_D - I_IN, kb = r / (DM / 32), nb_ = r % (DM / 32); transpose_item(ap->in[I_WOUT], DM, WOUT, DM, 64 * kb, 32 * nb_, 32 * nb_, scr, lane); } }
.LBB0_86:
	s_add_i32 s25, s14, s24
	s_cmpk_gt_i32 s25, 0x369f
	s_mov_b64 s[18:19], -1
	s_cbranch_scc1 .LBB0_85
	s_cmpk_gt_i32 s25, 0x157f
	s_cbranch_scc0 .LBB0_93
	s_cmpk_gt_u32 s25, 0x2e9f
	s_cbranch_scc0 .LBB0_90
	s_load_dwordx2 s[26:27], s[8:9], 0xc0
	s_add_i32 s18, s25, 0xffffd160
	s_and_b32 s14, s18, 0xffffffc0
	s_lshl_b32 s18, s18, 5
	s_and_b32 s18, s18, 0x7e0
	s_lshl_b32 s19, s18, 2
	s_waitcnt lgkmcnt(0)
	s_add_u32 s26, s26, s19
	s_addc_u32 s27, s27, 0
	v_or_b32_e32 v54, s14, v1
	v_mov_b32_e32 v55, v3
	v_lshl_add_u64 v[10:11], s[26:27], 0, v[2:3]
	v_lshlrev_b64 v[54:55], 13, v[54:55]
	v_or_b32_e32 v56, s14, v13
	v_mov_b32_e32 v57, v3
	v_or_b32_e32 v58, s14, v14
	v_mov_b32_e32 v59, v3
	v_or_b32_e32 v60, s14, v15
	v_mov_b32_e32 v61, v3
	v_or_b32_e32 v62, s14, v16
	v_mov_b32_e32 v63, v3
	v_or_b32_e32 v64, s14, v17
	v_mov_b32_e32 v65, v3
	v_or_b32_e32 v66, s14, v18
	v_mov_b32_e32 v67, v3
	v_or_b32_e32 v68, s14, v20
	v_mov_b32_e32 v69, v3
	v_lshl_add_u64 v[54:55], v[10:11], 0, v[54:55]
	v_lshlrev_b64 v[56:57], 13, v[56:57]
	v_lshlrev_b64 v[58:59], 13, v[58:59]
	v_lshlrev_b64 v[60:61], 13, v[60:61]
	v_lshlrev_b64 v[62:63], 13, v[62:63]
	v_lshlrev_b64 v[64:65], 13, v[64:65]
	v_lshlrev_b64 v[66:67], 13, v[66:67]
	v_lshlrev_b64 v[68:69], 13, v[68:69]
	v_lshl_add_u64 v[56:57], v[10:11], 0, v[56:57]
	v_lshl_add_u64 v[58:59], v[10:11], 0, v[58:59]
	v_lshl_add_u64 v[60:61], v[10:11], 0, v[60:61]
	v_lshl_add_u64 v[62:63], v[10:11], 0, v[62:63]
	v_lshl_add_u64 v[64:65], v[10:11], 0, v[64:65]
	v_lshl_add_u64 v[66:67], v[10:11], 0, v[66:67]
	v_lshl_add_u64 v[68:69], v[10:11], 0, v[68:69]
	global_load_dword v53, v[54:55], off
	global_load_dword v70, v[56:57], off
	global_load_dword v71, v[58:59], off
	global_load_dword v72, v[60:61], off
	global_load_dword v73, v[62:63], off
	global_load_dword v74, v[64:65], off
	global_load_dword v75, v[66:67], off
	global_load_dword v76, v[68:69], off
	v_or_b32_e32 v54, s14, v21
	v_mov_b32_e32 v55, v3
	v_lshlrev_b64 v[54:55], 13, v[54:55]
	v_or_b32_e32 v56, s14, v22
	v_mov_b32_e32 v57, v3
	v_or_b32_e32 v58, s14, v23
	v_mov_b32_e32 v59, v3
	v_or_b32_e32 v60, s14, v24
	v_mov_b32_e32 v61, v3
	v_or_b32_e32 v62, s14, v25
	v_mov_b32_e32 v63, v3
	v_or_b32_e32 v64, s14, v27
	v_mov_b32_e32 v65, v3
	v_or_b32_e32 v66, s14, v28
	v_mov_b32_e32 v67, v3
	v_or_b32_e32 v68, s14, v29
	v_mov_b32_e32 v69, v3
	v_lshl_add_u64 v[54:55], v[10:11], 0, v[54:55]
	v_lshlrev_b64 v[56:57], 13, v[56:57]
	v_lshlrev_b64 v[58:59], 13, v[58:59]
	v_lshlrev_b64 v[60:61], 13, v[60:61]
	v_lshlrev_b64 v[62:63], 13, v[62:63]
	v_lshlrev_b64 v[64:65], 13, v[64:65]
	v_lshlrev_b64 v[66:67], 13, v[66:67]
	v_lshlrev_b64 v[68:69], 13, v[68:69]
	v_lshl_add_u64 v[56:57], v[10:11], 0, v[56:57]
	v_lshl_add_u64 v[58:59], v[10:11], 0, v[58:59]
	v_lshl_add_u64 v[60:61], v[10:11], 0, v[60:61]
	v_lshl_add_u64 v[62:63], v[10:11], 0, v[62:63]
	v_lshl_add_u64 v[64:65], v[10:11], 0, v[64:65]
	v_lshl_add_u64 v[66:67], v[10:11], 0, v[66:67]
	v_lshl_add_u64 v[68:69], v[10:11], 0, v[68:69]
	global_load_dword v77, v[54:55], off
	global_load_dword v78, v[56:57], off
	global_load_dword v79, v[58:59], off
	global_load_dword v80, v[60:61], off
	global_load_dword v81, v[62:63], off
	global_load_dword v82, v[64:65], off
	global_load_dword v83, v[66:67], off
	global_load_dword v84, v[68:69], off
	v_or_b32_e32 v54, s14, v30
	v_mov_b32_e32 v55, v3
	v_lshlrev_b64 v[54:55], 13, v[54:55]
	v_or_b32_e32 v56, s14, v31
	v_mov_b32_e32 v57, v3
	v_or_b32_e32 v58, s14, v32
	v_mov_b32_e32 v59, v3
	v_or_b32_e32 v60, s14, v34
	v_mov_b32_e32 v61, v3
	v_or_b32_e32 v62, s14, v35
	v_mov_b32_e32 v63, v3
	v_or_b32_e32 v64, s14, v36
	v_mov_b32_e32 v65, v3
	v_or_b32_e32 v66, s14, v37
	v_mov_b32_e32 v67, v3
	v_or_b32_e32 v68, s14, v38
	v_mov_b32_e32 v69, v3
	v_lshl_add_u64 v[54:55], v[10:11], 0, v[54:55]
	v_lshlrev_b64 v[56:57], 13, v[56:57]
	v_lshlrev_b64 v[58:59], 13, v[58:59]
	v_lshlrev_b64 v[60:61], 13, v[60:61]
	v_lshlrev_b64 v[62:63], 13, v[62:63]
	v_lshlrev_b64 v[64:65], 13, v[64:65]
	v_lshlrev_b64 v[66:67], 13, v[66:67]
	v_lshlrev_b64 v[68:69], 13, v[68:69]
	v_lshl_add_u64 v[56:57], v[10:11], 0, v[56:57]
	v_lshl_add_u64 v[58:59], v[10:11], 0, v[58:59]
	v_lshl_add_u64 v[60:61], v[10:11], 0, v[60:61]
	v_lshl_add_u64 v[62:63], v[10:11], 0, v[62:63]
	v_lshl_add_u64 v[64:65], v[10:11], 0, v[64:65]
	v_lshl_add_u64 v[66:67], v[10:11], 0, v[66:67]
	v_lshl_add_u64 v[68:69], v[10:11], 0, v[68:69]
	global_load_dword v85, v[54:55], off
	global_load_dword v86, v[56:57], off
	global_load_dword v87, v[58:59], off
	global_load_dword v88, v[60:61], off
	global_load_dword v89, v[62:63], off
	global_load_dword v90, v[64:65], off
	global_load_dword v91, v[66:67], off
	global_load_dword v92, v[68:69], off
	v_or_b32_e32 v54, s14, v39
	v_mov_b32_e32 v55, v3
	v_lshlrev_b64 v[54:55], 13, v[54:55]
	v_or_b32_e32 v56, s14, v40
	v_mov_b32_e32 v57, v3
	v_or_b32_e32 v58, s14, v41
	v_mov_b32_e32 v59, v3
	v_or_b32_e32 v60, s14, v42
	v_mov_b32_e32 v61, v3
	v_or_b32_e32 v62, s14, v43
	v_mov_b32_e32 v63, v3
	v_or_b32_e32 v64, s14, v44
	v_mov_b32_e32 v65, v3
	v_or_b32_e32 v66, s14, v45
	v_mov_b32_e32 v67, v3
	v_or_b32_e32 v68, s14, v46
	v_mov_b32_e32 v69, v3
	v_lshl_add_u64 v[54:55], v[10:11], 0, v[54:55]
	v_lshlrev_b64 v[56:57], 13, v[56:57]
	v_lshlrev_b64 v[58:59], 13, v[58:59]
	v_lshlrev_b64 v[60:61], 13, v[60:61]
	v_lshlrev_b64 v[62:63], 13, v[62:63]
	v_lshlrev_b64 v[64:65], 13, v[64:65]
	v_lshlrev_b64 v[66:67], 13, v[66:67]
	v_lshlrev_b64 v[68:69], 13, v[68:69]
	v_lshl_add_u64 v[56:57], v[10:11], 0, v[56:57]
	v_lshl_add_u64 v[58:59], v[10:11], 0, v[58:59]
	v_lshl_add_u64 v[60:61], v[10:11], 0, v[60:61]
	v_lshl_add_u64 v[62:63], v[10:11], 0, v[62:63]
	v_lshl_add_u64 v[64:65], v[10:11], 0, v[64:65]
	v_lshl_add_u64 v[66:67], v[10:11], 0, v[66:67]
	v_lshl_add_u64 v[10:11], v[10:11], 0, v[68:69]
	global_load_dword v68, v[54:55], off
	global_load_dword v69, v[56:57], off
	global_load_dword v93, v[58:59], off
	global_load_dword v94, v[60:61], off
	global_load_dword v95, v[62:63], off
	global_load_dword v96, v[64:65], off
	global_load_dword v97, v[66:67], off
	global_load_dword v98, v[10:11], off
	v_add_u32_e32 v10, 0x400, v52
	s_waitcnt vmcnt(0)
; #define LAS __attribute__((address_space(3)))
; __device__ __forceinline__ unsigned pk2(float lo, float hi) { return pg8::cvt_pk_bf16(lo, hi); }
; __device__ __forceinline__ void transpose_item(const float* W, int N, bf16* WT, int ldk, int k0, int n0, int row_base, LAS float* scr, int lane) {
;     ...
;     for (int i = 0; i < 32; ++i) { const int kk = 2 * i + (lane >> 5); scr[kk * 33 + (lane & 31)] = W[(size_t)(k0 + kk) * N + n0 + (lane & 31)]; }
;     asm volatile("s_waitcnt lgkmcnt(0)" ::: "memory");
;     const int c = lane & 7;
; #pragma unroll
;     for (int j = 0; j < 4; ++j) { const int n = (lane >> 3) + 8 * j; const LAS float* s = scr + (8 * c) * 33 + n;
;         u32x4 o; o.x = pk2(s[0 * 33], s[1 * 33]); o.y = pk2(s[2 * 33], s[3 * 33]); o.z = pk2(s[4 * 33], s[5 * 33]); o.w = pk2(s[6 * 33], s[7 * 33]);
;         *(u32x4*)(WT + (size_t)(row_base + n) * ldk + k0 + 8 * c) = o; }
;     asm volatile("s_waitcnt lgkmcnt(0)" ::: "memory");
; __global__ void __launch_bounds__(NTHREADS, 2) fwd_kernel(Args args) {
;     ...
;                 else if (it < I_D + I_IN) { const int r = it - I_D, kb = r / (PROJ / 32), nb_ = r % (PROJ / 32); transpose_item(ap->in[I_WIN], PROJ, WIN, DM, 64 * kb, 32 * nb_, 32 * nb_, scr, lane); }
	ds_write2_b32 v52, v53, v70 offset1:66
	ds_write2_b32 v52, v71, v72 offset0:132 offset1:198
	ds_write2_b32 v10, v73, v74 offset0:8 offset1:74
	v_add_u32_e32 v10, v12, v19
	ds_write2_b32 v10, v75, v76 offset1:66
	ds_write2_b32 v10, v77, v78 offset0:132 offset1:198
	v_add_u32_e32 v10, 0x400, v10
	ds_write2_b32 v10, v79, v80 offset0:8 offset1:74
	v_add_u32_e32 v10, v12, v26
	ds_write2_b32 v10, v81, v82 offset1:66
	ds_write2_b32 v10, v83, v84 offset0:132 offset1:198
	v_add_u32_e32 v10, 0x400, v10
	v_or_b32_e32 v53, s18, v47
	v_lshl_add_u64 v[58:59], s[14:15], 1, v[4:5]
	v_lshlrev_b32_e32 v60, 12, v53
	v_mov_b32_e32 v61, v3
	v_lshl_add_u64 v[60:61], v[58:59], 0, v[60:61]
	v_or_b32_e32 v53, s18, v49
	ds_write2_b32 v10, v85, v86 offset0:8 offset1:74
	v_add_u32_e32 v10, v12, v33
	v_add_u32_e32 v11, 0x400, v10
	ds_write2_b32 v10, v87, v88 offset1:66
	ds_write2_b32 v10, v89, v90 offset0:132 offset1:198
	ds_write2_b32 v11, v91, v92 offset0:8 offset1:74
	ds_write2_b32 v11, v68, v69 offset0:140 offset1:206
	v_add_u32_e32 v11, 0x800, v10
	v_add_u32_e32 v10, 0xc00, v10
	ds_write2_b32 v11, v93, v94 offset0:16 offset1:82
	ds_write2_b32 v11, v95, v96 offset0:148 offset1:214
	ds_write2_b32 v10, v97, v98 offset0:24 offset1:90
	s_waitcnt lgkmcnt(0)
	ds_read2_b32 v[10:11], v48 offset1:33
	ds_read2_b32 v[68:69], v48 offset0:66 offset1:99
	ds_read2_b32 v[70:71], v48 offset0:132 offset1:165
	ds_read2_b32 v[72:73], v48 offset0:198 offset1:231
	ds_read2_b32 v[74:75], v48 offset0:8 offset1:41
	ds_read2_b32 v[76:77], v48 offset0:74 offset1:107
	ds_read2_b32 v[78:79], v48 offset0:140 offset1:173
	ds_read2_b32 v[80:81], v48 offset0:206 offset1:239
	ds_read2_b32 v[82:83], v48 offset0:16 offset1:49
	ds_read2_b32 v[84:85], v48 offset0:82 offset1:115
	ds_read2_b32 v[86:87], v48 offset0:148 offset1:181
	ds_read2_b32 v[88:89], v48 offset0:214 offset1:247
	ds_read2_b32 v[90:91], v48 offset0:24 offset1:57
	ds_read2_b32 v[92:93], v48 offset0:90 offset1:123
	ds_read2_b32 v[94:95], v48 offset0:156 offset1:189
	ds_read2_b32 v[96:97], v48 offset0:222 offset1:255
	s_waitcnt lgkmcnt(0)
	v_cvt_pk_bf16_f32 v54, v10, v11
	v_cvt_pk_bf16_f32 v55, v68, v69
	v_cvt_pk_bf16_f32 v56, v70, v71
	v_cvt_pk_bf16_f32 v57, v72, v73
	global_store_dwordx4 v[60:61], v[54:57], off
	s_nop 1
	v_lshlrev_b32_e32 v60, 12, v53
	v_mov_b32_e32 v61, v3
	v_cvt_pk_bf16_f32 v54, v74, v75
	v_cvt_pk_bf16_f32 v55, v76, v77
	v_cvt_pk_bf16_f32 v56, v78, v79
	v_cvt_pk_bf16_f32 v57, v80, v81
	v_lshl_add_u64 v[60:61], v[58:59], 0, v[60:61]
	global_store_dwordx4 v[60:61], v[54:57], off
	s_nop 1
	v_or_b32_e32 v53, s18, v50
	v_lshlrev_b32_e32 v60, 12, v53
	v_cvt_pk_bf16_f32 v54, v82, v83
	v_cvt_pk_bf16_f32 v55, v84, v85
	v_cvt_pk_bf16_f32 v56, v86, v87
	v_mov_b32_e32 v61, v3
	v_cvt_pk_bf16_f32 v57, v88, v89
	v_lshl_add_u64 v[60:61], v[58:59], 0, v[60:61]
	global_store_dwordx4 v[60:61], v[54:57], off
	s_nop 1
	s_nop 0
	v_cvt_pk_bf16_f32 v54, v90, v91
	v_cvt_pk_bf16_f32 v55, v92, v93
	v_cvt_pk_bf16_f32 v56, v94, v95
	v_cvt_pk_bf16_f32 v57, v96, v97
	v_or_b32_e32 v10, s18, v51
	v_lshlrev_b32_e32 v10, 12, v10
	v_mov_b32_e32 v11, v3
	v_lshl_add_u64 v[10:11], v[58:59], 0, v[10:11]
	global_store_dwordx4 v[10:11], v[54:57], off
	s_waitcnt lgkmcnt(0)
	s_mov_b64 s[18:19], 0
.LBB0_90:
	s_andn2_b64 vcc, exec, s[18:19]
	s_cbranch_vccnz .LBB0_92
	s_add_i32 s18, s25, 0xea80
	s_and_b32 s14, s18, 0xffff
	s_mul_i32 s14, s14, 0xa307
	s_lshr_b32 s14, s14, 23
	s_mul_i32 s19, s14, 0xc9
	s_sub_i32 s18, s18, s19
	s_lshl_b32 s19, s14, 6
	v_or_b32_e32 v53, s19, v1
	v_mul_u32_u24_e32 v53, 0x1920, v53
	v_lshlrev_b32_e32 v54, 2, v53
	v_or_b32_e32 v53, s19, v13
	v_mul_u32_u24_e32 v53, 0x1920, v53
	v_lshlrev_b32_e32 v56, 2, v53
	v_or_b32_e32 v53, s19, v14
	v_mul_u32_u24_e32 v53, 0x1920, v53
	v_lshlrev_b32_e32 v58, 2, v53
	v_or_b32_e32 v53, s19, v15
	v_mul_u32_u24_e32 v53, 0x1920, v53
	s_load_dwordx2 s[26:27], s[8:9], 0x58
	v_lshlrev_b32_e32 v60, 2, v53
	v_or_b32_e32 v53, s19, v16
	v_mul_u32_u24_e32 v53, 0x1920, v53
	s_lshl_b32 s18, s18, 5
	v_lshlrev_b32_e32 v62, 2, v53
	v_or_b32_e32 v53, s19, v17
	s_and_b32 s18, s18, 0xffe0
	v_mul_u32_u24_e32 v53, 0x1920, v53
	s_lshl_b32 s28, s18, 2
	v_lshlrev_b32_e32 v64, 2, v53
	v_or_b32_e32 v53, s19, v18
	s_waitcnt lgkmcnt(0)
	s_add_u32 s26, s26, s28
	v_mul_u32_u24_e32 v53, 0x1920, v53
	s_addc_u32 s27, s27, 0
	v_lshlrev_b32_e32 v66, 2, v53
	v_or_b32_e32 v53, s19, v20
	v_lshl_add_u64 v[10:11], s[26:27], 0, v[2:3]
	v_mov_b32_e32 v55, v3
	v_mul_u32_u24_e32 v53, 0x1920, v53
	v_lshl_add_u64 v[54:55], v[10:11], 0, v[54:55]
	v_mov_b32_e32 v57, v3
	v_mov_b32_e32 v59, v3
	v_mov_b32_e32 v61, v3
	v_mov_b32_e32 v63, v3
	v_mov_b32_e32 v65, v3
	v_mov_b32_e32 v67, v3
	v_lshlrev_b32_e32 v68, 2, v53
	v_mov_b32_e32 v69, v3
	v_lshl_add_u64 v[56:57], v[10:11], 0, v[56:57]
	v_lshl_add_u64 v[58:59], v[10:11], 0, v[58:59]
	v_lshl_add_u64 v[60:61], v[10:11], 0, v[60:61]
	v_lshl_add_u64 v[62:63], v[10:11], 0, v[62:63]
	v_lshl_add_u64 v[64:65], v[10:11], 0, v[64:65]
	v_lshl_add_u64 v[66:67], v[10:11], 0, v[66:67]
	v_lshl_add_u64 v[68:69], v[10:11], 0, v[68:69]
	global_load_dword v53, v[54:55], off
	global_load_dword v70, v[56:57], off
	global_load_dword v71, v[58:59], off
	global_load_dword v72, v[60:61], off
	global_load_dword v73, v[62:63], off
	global_load_dword v74, v[64:65], off
	global_load_dword v75, v[66:67], off
	global_load_dword v76, v[68:69], off
	v_or_b32_e32 v54, s19, v21
	v_mul_u32_u24_e32 v54, 0x1920, v54
	v_or_b32_e32 v56, s19, v22
	v_or_b32_e32 v58, s19, v23
	v_or_b32_e32 v60, s19, v24
	v_or_b32_e32 v62, s19, v25
	v_or_b32_e32 v64, s19, v27
	v_or_b32_e32 v66, s19, v28
	v_or_b32_e32 v68, s19, v29
	v_lshlrev_b32_e32 v54, 2, v54
; #define LAS __attribute__((address_space(3)))
; __device__ __forceinline__ void transpose_item(const float* W, int N, bf16* WT, int ldk, int k0, int n0, int row_base, LAS float* scr, int lane) {
; #pragma unroll
;     for (int i = 0; i < 32; ++i) { const int kk = 2 * i + (lane >> 5); scr[kk * 33 + (lane & 31)] = W[(size_t)(k0 + kk) * N + n0 + (lane & 31)]; }
	v_mov_b32_e32 v55, v3
	v_mul_u32_u24_e32 v56, 0x1920, v56
	v_mul_u32_u24_e32 v58, 0x1920, v58
	v_mul_u32_u24_e32 v60, 0x1920, v60
	v_mul_u32_u24_e32 v62, 0x1920, v62
	v_mul_u32_u24_e32 v64, 0x1920, v64
	v_mul_u32_u24_e32 v66, 0x1920, v66
	v_mul_u32_u24_e32 v68, 0x1920, v68
	v_lshl_add_u64 v[54:55], v[10:11], 0, v[54:55]
	v_lshlrev_b32_e32 v56, 2, v56
	v_mov_b32_e32 v57, v3
	v_lshlrev_b32_e32 v58, 2, v58
	v_mov_b32_e32 v59, v3
	v_lshlrev_b32_e32 v60, 2, v60
	v_mov_b32_e32 v61, v3
	v_lshlrev_b32_e32 v62, 2, v62
	v_mov_b32_e32 v63, v3
	v_lshlrev_b32_e32 v64, 2, v64
	v_mov_b32_e32 v65, v3
	v_lshlrev_b32_e32 v66, 2, v66
	v_mov_b32_e32 v67, v3
	v_lshlrev_b32_e32 v68, 2, v68
	v_mov_b32_e32 v69, v3
	v_lshl_add_u64 v[56:57], v[10:11], 0, v[56:57]
	v_lshl_add_u64 v[58:59], v[10:11], 0, v[58:59]
	v_lshl_add_u64 v[60:61], v[10:11], 0, v[60:61]
	v_lshl_add_u64 v[62:63], v[10:11], 0, v[62:63]
	v_lshl_add_u64 v[64:65], v[10:11], 0, v[64:65]
	v_lshl_add_u64 v[66:67], v[10:11], 0, v[66:67]
	v_lshl_add_u64 v[68:69], v[10:11], 0, v[68:69]
	global_load_dword v77, v[54:55], off
	global_load_dword v78, v[56:57], off
	global_load_dword v79, v[58:59], off
	global_load_dword v80, v[60:61], off
	global_load_dword v81, v[62:63], off
	global_load_dword v82, v[64:65], off
	global_load_dword v83, v[66:67], off
	global_load_dword v84, v[68:69], off
	v_or_b32_e32 v54, s19, v30
	v_mul_u32_u24_e32 v54, 0x1920, v54
	v_or_b32_e32 v56, s19, v31
	v_or_b32_e32 v58, s19, v32
	v_or_b32_e32 v60, s19, v34
	v_or_b32_e32 v62, s19, v35
	v_or_b32_e32 v64, s19, v36
	v_or_b32_e32 v66, s19, v37
	v_or_b32_e32 v68, s19, v38
	v_lshlrev_b32_e32 v54, 2, v54
	v_mov_b32_e32 v55, v3
	v_mul_u32_u24_e32 v56, 0x1920, v56
	v_mul_u32_u24_e32 v58, 0x1920, v58
	v_mul_u32_u24_e32 v60, 0x1920, v60
	v_mul_u32_u24_e32 v62, 0x1920, v62
	v_mul_u32_u24_e32 v64, 0x1920, v64
	v_mul_u32_u24_e32 v66, 0x1920, v66
	v_mul_u32_u24_e32 v68, 0x1920, v68
	v_lshl_add_u64 v[54:55], v[10:11], 0, v[54:55]
	v_lshlrev_b32_e32 v56, 2, v56
	v_mov_b32_e32 v57, v3
	v_lshlrev_b32_e32 v58, 2, v58
	v_mov_b32_e32 v59, v3
	v_lshlrev_b32_e32 v60, 2, v60
	v_mov_b32_e32 v61, v3
	v_lshlrev_b32_e32 v62, 2, v62
	v_mov_b32_e32 v63, v3
	v_lshlrev_b32_e32 v64, 2, v64
	v_mov_b32_e32 v65, v3
	v_lshlrev_b32_e32 v66, 2, v66
	v_mov_b32_e32 v67, v3
	v_lshlrev_b32_e32 v68, 2, v68
	v_mov_b32_e32 v69, v3
	v_lshl_add_u64 v[56:57], v[10:11], 0, v[56:57]
	v_lshl_add_u64 v[58:59], v[10:11], 0, v[58:59]
	v_lshl_add_u64 v[60:61], v[10:11], 0, v[60:61]
	v_lshl_add_u64 v[62:63], v[10:11], 0, v[62:63]
	v_lshl_add_u64 v[64:65], v[10:11], 0, v[64:65]
	v_lshl_add_u64 v[66:67], v[10:11], 0, v[66:67]
	v_lshl_add_u64 v[68:69], v[10:11], 0, v[68:69]
	global_load_dword v85, v[54:55], off
	global_load_dword v86, v[56:57], off
	global_load_dword v87, v[58:59], off
	global_load_dword v88, v[60:61], off
	global_load_dword v89, v[62:63], off
	global_load_dword v90, v[64:65], off
	global_load_dword v91, v[66:67], off
	global_load_dword v92, v[68:69], off
	v_or_b32_e32 v54, s19, v39
	v_mul_u32_u24_e32 v54, 0x1920, v54
	v_or_b32_e32 v56, s19, v40
	v_or_b32_e32 v58, s19, v41
	v_or_b32_e32 v60, s19, v42
	v_or_b32_e32 v62, s19, v43
	v_or_b32_e32 v64, s19, v44
	v_or_b32_e32 v66, s19, v45
	v_or_b32_e32 v68, s19, v46
	v_lshlrev_b32_e32 v54, 2, v54
	v_mov_b32_e32 v55, v3
	v_mul_u32_u24_e32 v56, 0x1920, v56
	v_mul_u32_u24_e32 v58, 0x1920, v58
	v_mul_u32_u24_e32 v60, 0x1920, v60
	v_mul_u32_u24_e32 v62, 0x1920, v62
	v_mul_u32_u24_e32 v64, 0x1920, v64
	v_mul_u32_u24_e32 v66, 0x1920, v66
	v_mul_u32_u24_e32 v68, 0x1920, v68
	v_lshl_add_u64 v[54:55], v[10:11], 0, v[54:55]
	v_lshlrev_b32_e32 v56, 2, v56
	v_mov_b32_e32 v57, v3
	v_lshlrev_b32_e32 v58, 2, v58
	v_mov_b32_e32 v59, v3
	v_lshlrev_b32_e32 v60, 2, v60
	v_mov_b32_e32 v61, v3
	v_lshlrev_b32_e32 v62, 2, v62
	v_mov_b32_e32 v63, v3
	v_lshlrev_b32_e32 v64, 2, v64
	v_mov_b32_e32 v65, v3
	v_lshlrev_b32_e32 v66, 2, v66
	v_mov_b32_e32 v67, v3
	v_lshlrev_b32_e32 v68, 2, v68
	v_mov_b32_e32 v69, v3
	v_lshl_add_u64 v[56:57], v[10:11], 0, v[56:57]
	v_lshl_add_u64 v[58:59], v[10:11], 0, v[58:59]
	v_lshl_add_u64 v[60:61], v[10:11], 0, v[60:61]
	v_lshl_add_u64 v[62:63], v[10:11], 0, v[62:63]
	v_lshl_add_u64 v[64:65], v[10:11], 0, v[64:65]
	v_lshl_add_u64 v[66:67], v[10:11], 0, v[66:67]
	v_lshl_add_u64 v[10:11], v[10:11], 0, v[68:69]
	global_load_dword v68, v[54:55], off
	global_load_dword v69, v[56:57], off
	global_load_dword v93, v[58:59], off
	global_load_dword v94, v[60:61], off
	global_load_dword v95, v[62:63], off
	global_load_dword v96, v[64:65], off
	global_load_dword v97, v[66:67], off
	global_load_dword v98, v[10:11], off
	v_add_u32_e32 v10, 0x400, v52
	s_waitcnt vmcnt(0)
; #define LAS __attribute__((address_space(3)))
; __device__ __forceinline__ unsigned pk2(float lo, float hi) { return pg8::cvt_pk_bf16(lo, hi); }
; __device__ __forceinline__ void transpose_item(const float* W, int N, bf16* WT, int ldk, int k0, int n0, int row_base, LAS float* scr, int lane) {
;     ...
;     for (int i = 0; i < 32; ++i) { const int kk = 2 * i + (lane >> 5); scr[kk * 33 + (lane & 31)] = W[(size_t)(k0 + kk) * N + n0 + (lane & 31)]; }
;     asm volatile("s_waitcnt lgkmcnt(0)" ::: "memory");
;     const int c = lane & 7;
; #pragma unroll
;     for (int j = 0; j < 4; ++j) { const int n = (lane >> 3) + 8 * j; const LAS float* s = scr + (8 * c) * 33 + n;
;         u32x4 o; o.x = pk2(s[0 * 33], s[1 * 33]); o.y = pk2(s[2 * 33], s[3 * 33]); o.z = pk2(s[4 * 33], s[5 * 33]); o.w = pk2(s[6 * 33], s[7 * 33]);
;         *(u32x4*)(WT + (size_t)(row_base + n) * ldk + k0 + 8 * c) = o; }
;     asm volatile("s_waitcnt lgkmcnt(0)" ::: "memory");
	ds_write2_b32 v52, v53, v70 offset1:66
	ds_write2_b32 v52, v71, v72 offset0:132 offset1:198
	ds_write2_b32 v10, v73, v74 offset0:8 offset1:74
	v_add_u32_e32 v10, v12, v19
	ds_write2_b32 v10, v75, v76 offset1:66
	ds_write2_b32 v10, v77, v78 offset0:132 offset1:198
	v_add_u32_e32 v10, 0x400, v10
	ds_write2_b32 v10, v79, v80 offset0:8 offset1:74
	v_add_u32_e32 v10, v12, v26
	ds_write2_b32 v10, v81, v82 offset1:66
	ds_write2_b32 v10, v83, v84 offset0:132 offset1:198
	v_add_u32_e32 v10, 0x400, v10
	s_lshl_b32 s14, s14, 7
	v_or_b32_e32 v53, s18, v47
	v_lshl_add_u64 v[58:59], v[6:7], 0, s[14:15]
	v_lshlrev_b32_e32 v60, 12, v53
	v_mov_b32_e32 v61, v3
	v_lshl_add_u64 v[60:61], v[58:59], 0, v[60:61]
	v_or_b32_e32 v53, s18, v49
	ds_write2_b32 v10, v85, v86 offset0:8 offset1:74
	v_add_u32_e32 v10, v12, v33
	v_add_u32_e32 v11, 0x400, v10
	ds_write2_b32 v10, v87, v88 offset1:66
	ds_write2_b32 v10, v89, v90 offset0:132 offset1:198
	ds_write2_b32 v11, v91, v92 offset0:8 offset1:74
	ds_write2_b32 v11, v68, v69 offset0:140 offset1:206
	v_add_u32_e32 v11, 0x800, v10
	v_add_u32_e32 v10, 0xc00, v10
	ds_write2_b32 v11, v93, v94 offset0:16 offset1:82
	ds_write2_b32 v11, v95, v96 offset0:148 offset1:214
	ds_write2_b32 v10, v97, v98 offset0:24 offset1:90
	s_waitcnt lgkmcnt(0)
	ds_read2_b32 v[10:11], v48 offset1:33
	ds_read2_b32 v[68:69], v48 offset0:66 offset1:99
	ds_read2_b32 v[70:71], v48 offset0:132 offset1:165
	ds_read2_b32 v[72:73], v48 offset0:198 offset1:231
	ds_read2_b32 v[74:75], v48 offset0:8 offset1:41
	ds_read2_b32 v[76:77], v48 offset0:74 offset1:107
	ds_read2_b32 v[78:79], v48 offset0:140 offset1:173
	ds_read2_b32 v[80:81], v48 offset0:206 offset1:239
	ds_read2_b32 v[82:83], v48 offset0:16 offset1:49
	ds_read2_b32 v[84:85], v48 offset0:82 offset1:115
	ds_read2_b32 v[86:87], v48 offset0:148 offset1:181
	ds_read2_b32 v[88:89], v48 offset0:214 offset1:247
	ds_read2_b32 v[90:91], v48 offset0:24 offset1:57
	ds_read2_b32 v[92:93], v48 offset0:90 offset1:123
	ds_read2_b32 v[94:95], v48 offset0:156 offset1:189
	ds_read2_b32 v[96:97], v48 offset0:222 offset1:255
	s_waitcnt lgkmcnt(0)
	v_cvt_pk_bf16_f32 v54, v10, v11
	v_cvt_pk_bf16_f32 v55, v68, v69
	v_cvt_pk_bf16_f32 v56, v70, v71
	v_cvt_pk_bf16_f32 v57, v72, v73
	global_store_dwordx4 v[60:61], v[54:57], off
	s_nop 1
	v_lshlrev_b32_e32 v60, 12, v53
	v_mov_b32_e32 v61, v3
	v_cvt_pk_bf16_f32 v54, v74, v75
	v_cvt_pk_bf16_f32 v55, v76, v77
	v_cvt_pk_bf16_f32 v56, v78, v79
	v_cvt_pk_bf16_f32 v57, v80, v81
	v_lshl_add_u64 v[60:61], v[58:59], 0, v[60:61]
	global_store_dwordx4 v[60:61], v[54:57], off
	s_nop 1
	v_or_b32_e32 v53, s18, v50
	v_lshlrev_b32_e32 v60, 12, v53
	v_cvt_pk_bf16_f32 v54, v82, v83
	v_cvt_pk_bf16_f32 v55, v84, v85
	v_cvt_pk_bf16_f32 v56, v86, v87
	v_mov_b32_e32 v61, v3
	v_cvt_pk_bf16_f32 v57, v88, v89
	v_lshl_add_u64 v[60:61], v[58:59], 0, v[60:61]
	global_store_dwordx4 v[60:61], v[54:57], off
	s_nop 1
	s_nop 0
	v_cvt_pk_bf16_f32 v54, v90, v91
	v_cvt_pk_bf16_f32 v55, v92, v93
	v_cvt_pk_bf16_f32 v56, v94, v95
	v_cvt_pk_bf16_f32 v57, v96, v97
	v_or_b32_e32 v10, s18, v51
	v_lshlrev_b32_e32 v10, 12, v10
	v_mov_b32_e32 v11, v3
	v_lshl_add_u64 v[10:11], v[58:59], 0, v[10:11]
	global_store_dwordx4 v[10:11], v[54:57], off
	s_waitcnt lgkmcnt(0)

; #define LAS __attribute__((address_space(3)))
; __device__ __forceinline__ void transpose_item(const float* W, int N, bf16* WT, int ldk, int k0, int n0, int row_base, LAS float* scr, int lane) {
; #pragma unroll
;     for (int i = 0; i < 32; ++i) { const int kk = 2 * i + (lane >> 5); scr[kk * 33 + (lane & 31)] = W[(size_t)(k0 + kk) * N + n0 + (lane & 31)]; }
; __global__ void __launch_bounds__(NTHREADS, 2) fwd_kernel(Args args) {
;     ...
;                 if (it < I_D) { const int kb = it / (DM / 32), nb_ = it % (DM / 32); transpose_item(ap->in[I_W1D], DM, WD, FF, 64 * kb, 32 * nb_, 32 * nb_, scr, lane); }
.LBB0_93:
	s_andn2_b64 vcc, exec, s[18:19]
	s_xor_b64 s[18:19], s[12:13], -1
	s_cbranch_vccnz .LBB0_85
	s_and_b32 s13, s25, 0x7fc0
	s_load_dwordx2 s[26:27], s[8:9], 0x40
	v_or_b32_e32 v53, s13, v1
	v_lshlrev_b32_e32 v54, 13, v53
	v_or_b32_e32 v53, s13, v13
	s_lshl_b32 s12, s25, 5
	v_lshlrev_b32_e32 v56, 13, v53
	v_or_b32_e32 v53, s13, v14
	s_and_b32 s12, s12, 0x7e0
	v_lshlrev_b32_e32 v58, 13, v53
	v_or_b32_e32 v53, s13, v15
	s_lshl_b32 s14, s12, 2
	v_lshlrev_b32_e32 v60, 13, v53
	v_or_b32_e32 v53, s13, v16
	s_waitcnt lgkmcnt(0)
	s_add_u32 s26, s26, s14
	v_lshlrev_b32_e32 v62, 13, v53
	v_or_b32_e32 v53, s13, v17
	s_addc_u32 s27, s27, 0
	v_lshlrev_b32_e32 v64, 13, v53
	v_or_b32_e32 v53, s13, v18
	v_lshl_add_u64 v[10:11], s[26:27], 0, v[2:3]
	v_mov_b32_e32 v55, v3
	v_lshlrev_b32_e32 v66, 13, v53
	v_or_b32_e32 v53, s13, v20
	v_lshl_add_u64 v[54:55], v[10:11], 0, v[54:55]
	v_mov_b32_e32 v57, v3
	v_mov_b32_e32 v59, v3
	v_mov_b32_e32 v61, v3
	v_mov_b32_e32 v63, v3
	v_mov_b32_e32 v65, v3
	v_mov_b32_e32 v67, v3
	v_lshlrev_b32_e32 v68, 13, v53
	v_mov_b32_e32 v69, v3
	v_lshl_add_u64 v[56:57], v[10:11], 0, v[56:57]
	v_lshl_add_u64 v[58:59], v[10:11], 0, v[58:59]
	v_lshl_add_u64 v[60:61], v[10:11], 0, v[60:61]
	v_lshl_add_u64 v[62:63], v[10:11], 0, v[62:63]
	v_lshl_add_u64 v[64:65], v[10:11], 0, v[64:65]
	v_lshl_add_u64 v[66:67], v[10:11], 0, v[66:67]
	v_lshl_add_u64 v[68:69], v[10:11], 0, v[68:69]
	global_load_dword v53, v[54:55], off
	global_load_dword v70, v[56:57], off
	global_load_dword v71, v[58:59], off
	global_load_dword v72, v[60:61], off
	global_load_dword v73, v[62:63], off
	global_load_dword v74, v[64:65], off
	global_load_dword v75, v[66:67], off
	global_load_dword v76, v[68:69], off
	v_or_b32_e32 v54, s13, v21
	v_lshlrev_b32_e32 v54, 13, v54
	v_mov_b32_e32 v55, v3
	v_or_b32_e32 v56, s13, v22
	v_or_b32_e32 v58, s13, v23
	v_or_b32_e32 v60, s13, v24
	v_or_b32_e32 v62, s13, v25
	v_or_b32_e32 v64, s13, v27
	v_or_b32_e32 v66, s13, v28
	v_or_b32_e32 v68, s13, v29
	v_lshl_add_u64 v[54:55], v[10:11], 0, v[54:55]
	v_lshlrev_b32_e32 v56, 13, v56
	v_mov_b32_e32 v57, v3
	v_lshlrev_b32_e32 v58, 13, v58
	v_mov_b32_e32 v59, v3
	v_lshlrev_b32_e32 v60, 13, v60
	v_mov_b32_e32 v61, v3
	v_lshlrev_b32_e32 v62, 13, v62
	v_mov_b32_e32 v63, v3
	v_lshlrev_b32_e32 v64, 13, v64
	v_mov_b32_e32 v65, v3
	v_lshlrev_b32_e32 v66, 13, v66
	v_mov_b32_e32 v67, v3
	v_lshlrev_b32_e32 v68, 13, v68
	v_mov_b32_e32 v69, v3
	v_lshl_add_u64 v[56:57], v[10:11], 0, v[56:57]
	v_lshl_add_u64 v[58:59], v[10:11], 0, v[58:59]
	v_lshl_add_u64 v[60:61], v[10:11], 0, v[60:61]
	v_lshl_add_u64 v[62:63], v[10:11], 0, v[62:63]
	v_lshl_add_u64 v[64:65], v[10:11], 0, v[64:65]
	v_lshl_add_u64 v[66:67], v[10:11], 0, v[66:67]
	v_lshl_add_u64 v[68:69], v[10:11], 0, v[68:69]
	global_load_dword v77, v[54:55], off
	global_load_dword v78, v[56:57], off
	global_load_dword v79, v[58:59], off
	global_load_dword v80, v[60:61], off
	global_load_dword v81, v[62:63], off
	global_load_dword v82, v[64:65], off
	global_load_dword v83, v[66:67], off
	global_load_dword v84, v[68:69], off
	v_or_b32_e32 v54, s13, v30
	v_lshlrev_b32_e32 v54, 13, v54
	v_mov_b32_e32 v55, v3
	v_or_b32_e32 v56, s13, v31
	v_or_b32_e32 v58, s13, v32
	v_or_b32_e32 v60, s13, v34
	v_or_b32_e32 v62, s13, v35
	v_or_b32_e32 v64, s13, v36
	v_or_b32_e32 v66, s13, v37
	v_or_b32_e32 v68, s13, v38
	v_lshl_add_u64 v[54:55], v[10:11], 0, v[54:55]
	v_lshlrev_b32_e32 v56, 13, v56
	v_mov_b32_e32 v57, v3
	v_lshlrev_b32_e32 v58, 13, v58
	v_mov_b32_e32 v59, v3
	v_lshlrev_b32_e32 v60, 13, v60
	v_mov_b32_e32 v61, v3
	v_lshlrev_b32_e32 v62, 13, v62
	v_mov_b32_e32 v63, v3
	v_lshlrev_b32_e32 v64, 13, v64
	v_mov_b32_e32 v65, v3
	v_lshlrev_b32_e32 v66, 13, v66
	v_mov_b32_e32 v67, v3
	v_lshlrev_b32_e32 v68, 13, v68
	v_mov_b32_e32 v69, v3
	v_lshl_add_u64 v[56:57], v[10:11], 0, v[56:57]
	v_lshl_add_u64 v[58:59], v[10:11], 0, v[58:59]
	v_lshl_add_u64 v[60:61], v[10:11], 0, v[60:61]
	v_lshl_add_u64 v[62:63], v[10:11], 0, v[62:63]
	v_lshl_add_u64 v[64:65], v[10:11], 0, v[64:65]
	v_lshl_add_u64 v[66:67], v[10:11], 0, v[66:67]
	v_lshl_add_u64 v[68:69], v[10:11], 0, v[68:69]
	global_load_dword v85, v[54:55], off
	global_load_dword v86, v[56:57], off
	global_load_dword v87, v[58:59], off
	global_load_dword v88, v[60:61], off
	global_load_dword v89, v[62:63], off
	global_load_dword v90, v[64:65], off
	global_load_dword v91, v[66:67], off
	global_load_dword v92, v[68:69], off
	v_or_b32_e32 v54, s13, v39
	v_lshlrev_b32_e32 v54, 13, v54
	v_mov_b32_e32 v55, v3
	v_or_b32_e32 v56, s13, v40
	v_or_b32_e32 v58, s13, v41
	v_or_b32_e32 v60, s13, v42
	v_or_b32_e32 v62, s13, v43
	v_or_b32_e32 v64, s13, v44
	v_or_b32_e32 v66, s13, v45
	v_or_b32_e32 v68, s13, v46
	v_lshl_add_u64 v[54:55], v[10:11], 0, v[54:55]
	v_lshlrev_b32_e32 v56, 13, v56
	v_mov_b32_e32 v57, v3
	v_lshlrev_b32_e32 v58, 13, v58
	v_mov_b32_e32 v59, v3
	v_lshlrev_b32_e32 v60, 13, v60
	v_mov_b32_e32 v61, v3
	v_lshlrev_b32_e32 v62, 13, v62
	v_mov_b32_e32 v63, v3
	v_lshlrev_b32_e32 v64, 13, v64
	v_mov_b32_e32 v65, v3
	v_lshlrev_b32_e32 v66, 13, v66
	v_mov_b32_e32 v67, v3
	v_lshlrev_b32_e32 v68, 13, v68
	v_mov_b32_e32 v69, v3
	v_lshl_add_u64 v[56:57], v[10:11], 0, v[56:57]
	v_lshl_add_u64 v[58:59], v[10:11], 0, v[58:59]
	v_lshl_add_u64 v[60:61], v[10:11], 0, v[60:61]
	v_lshl_add_u64 v[62:63], v[10:11], 0, v[62:63]
	v_lshl_add_u64 v[64:65], v[10:11], 0, v[64:65]
	v_lshl_add_u64 v[66:67], v[10:11], 0, v[66:67]
	v_lshl_add_u64 v[10:11], v[10:11], 0, v[68:69]
	global_load_dword v68, v[54:55], off
	global_load_dword v69, v[56:57], off
	global_load_dword v93, v[58:59], off
	global_load_dword v94, v[60:61], off
	global_load_dword v95, v[62:63], off
	global_load_dword v96, v[64:65], off
	global_load_dword v97, v[66:67], off
	global_load_dword v98, v[10:11], off
	v_add_u32_e32 v10, 0x400, v52
	s_waitcnt vmcnt(0)
; #define LAS __attribute__((address_space(3)))
; __device__ __forceinline__ unsigned pk2(float lo, float hi) { return pg8::cvt_pk_bf16(lo, hi); }
; __device__ __forceinline__ void transpose_item(const float* W, int N, bf16* WT, int ldk, int k0, int n0, int row_base, LAS float* scr, int lane) {
;     ...
;     for (int i = 0; i < 32; ++i) { const int kk = 2 * i + (lane >> 5); scr[kk * 33 + (lane & 31)] = W[(size_t)(k0 + kk) * N + n0 + (lane & 31)]; }
;     asm volatile("s_waitcnt lgkmcnt(0)" ::: "memory");
;     const int c = lane & 7;
; #pragma unroll
;     for (int j = 0; j < 4; ++j) { const int n = (lane >> 3) + 8 * j; const LAS float* s = scr + (8 * c) * 33 + n;
;         u32x4 o; o.x = pk2(s[0 * 33], s[1 * 33]); o.y = pk2(s[2 * 33], s[3 * 33]); o.z = pk2(s[4 * 33], s[5 * 33]); o.w = pk2(s[6 * 33], s[7 * 33]);
;         *(u32x4*)(WT + (size_t)(row_base + n) * ldk + k0 + 8 * c) = o; }
;     asm volatile("s_waitcnt lgkmcnt(0)" ::: "memory");
	ds_write2_b32 v52, v53, v70 offset1:66
	ds_write2_b32 v52, v71, v72 offset0:132 offset1:198
	ds_write2_b32 v10, v73, v74 offset0:8 offset1:74
	v_add_u32_e32 v10, v12, v19
	ds_write2_b32 v10, v75, v76 offset1:66
	ds_write2_b32 v10, v77, v78 offset0:132 offset1:198
	v_add_u32_e32 v10, 0x400, v10
	ds_write2_b32 v10, v79, v80 offset0:8 offset1:74
	v_add_u32_e32 v10, v12, v26
	ds_write2_b32 v10, v81, v82 offset1:66
	ds_write2_b32 v10, v83, v84 offset0:132 offset1:198
	v_add_u32_e32 v10, 0x400, v10
	s_lshl_b32 s14, s13, 1
	v_lshl_add_u64 v[58:59], v[8:9], 0, s[14:15]
	v_mov_b32_e32 v61, v3
	ds_write2_b32 v10, v85, v86 offset0:8 offset1:74
	v_add_u32_e32 v10, v12, v33
	v_add_u32_e32 v11, 0x400, v10
	ds_write2_b32 v10, v87, v88 offset1:66
	ds_write2_b32 v10, v89, v90 offset0:132 offset1:198
	ds_write2_b32 v11, v91, v92 offset0:8 offset1:74
	ds_write2_b32 v11, v68, v69 offset0:140 offset1:206
	v_add_u32_e32 v11, 0x800, v10
	v_add_u32_e32 v10, 0xc00, v10
	ds_write2_b32 v11, v93, v94 offset0:16 offset1:82
	ds_write2_b32 v11, v95, v96 offset0:148 offset1:214
	ds_write2_b32 v10, v97, v98 offset0:24 offset1:90
	s_waitcnt lgkmcnt(0)
	ds_read2_b32 v[10:11], v48 offset1:33
	ds_read2_b32 v[68:69], v48 offset0:66 offset1:99
	ds_read2_b32 v[70:71], v48 offset0:132 offset1:165
	ds_read2_b32 v[72:73], v48 offset0:198 offset1:231
	ds_read2_b32 v[74:75], v48 offset0:8 offset1:41
	ds_read2_b32 v[76:77], v48 offset0:74 offset1:107
	ds_read2_b32 v[78:79], v48 offset0:140 offset1:173
	ds_read2_b32 v[80:81], v48 offset0:206 offset1:239
	ds_read2_b32 v[82:83], v48 offset0:16 offset1:49
	ds_read2_b32 v[84:85], v48 offset0:82 offset1:115
	ds_read2_b32 v[86:87], v48 offset0:148 offset1:181
	ds_read2_b32 v[88:89], v48 offset0:214 offset1:247
	ds_read2_b32 v[90:91], v48 offset0:24 offset1:57
	ds_read2_b32 v[92:93], v48 offset0:90 offset1:123
	ds_read2_b32 v[94:95], v48 offset0:156 offset1:189
	ds_read2_b32 v[96:97], v48 offset0:222 offset1:255
	s_waitcnt lgkmcnt(0)
	v_cvt_pk_bf16_f32 v54, v10, v11
	v_cvt_pk_bf16_f32 v55, v68, v69
	v_cvt_pk_bf16_f32 v56, v70, v71
	v_cvt_pk_bf16_f32 v57, v72, v73
	v_or_b32_e32 v10, s12, v47
	v_mul_u32_u24_e32 v53, 0x1580, v10
	v_lshlrev_b32_e32 v60, 1, v53
	v_lshl_add_u64 v[60:61], v[58:59], 0, v[60:61]
	global_store_dwordx4 v[60:61], v[54:57], off
	s_nop 1
	v_mov_b32_e32 v61, v3
	v_cvt_pk_bf16_f32 v54, v74, v75
	v_cvt_pk_bf16_f32 v55, v76, v77
	v_cvt_pk_bf16_f32 v56, v78, v79
	v_cvt_pk_bf16_f32 v57, v80, v81
	v_or_b32_e32 v10, s12, v49
	v_mul_u32_u24_e32 v53, 0x1580, v10
	v_lshlrev_b32_e32 v60, 1, v53
	v_lshl_add_u64 v[60:61], v[58:59], 0, v[60:61]
	global_store_dwordx4 v[60:61], v[54:57], off
	s_nop 1
	v_mov_b32_e32 v61, v3
	v_cvt_pk_bf16_f32 v54, v82, v83
	v_cvt_pk_bf16_f32 v55, v84, v85
	v_cvt_pk_bf16_f32 v56, v86, v87
	v_cvt_pk_bf16_f32 v57, v88, v89
	v_or_b32_e32 v10, s12, v50
	v_mul_u32_u24_e32 v53, 0x1580, v10
	v_lshlrev_b32_e32 v60, 1, v53
	v_lshl_add_u64 v[60:61], v[58:59], 0, v[60:61]
	global_store_dwordx4 v[60:61], v[54:57], off
	s_nop 1
	s_nop 0
	v_cvt_pk_bf16_f32 v54, v90, v91
	v_cvt_pk_bf16_f32 v55, v92, v93
	v_cvt_pk_bf16_f32 v56, v94, v95
	v_cvt_pk_bf16_f32 v57, v96, v97
	v_or_b32_e32 v10, s12, v51
	v_mul_u32_u24_e32 v10, 0x1580, v10
	v_lshlrev_b32_e32 v10, 1, v10
	v_mov_b32_e32 v11, v3
	v_lshl_add_u64 v[10:11], v[58:59], 0, v[10:11]
	global_store_dwordx4 v[10:11], v[54:57], off
	s_waitcnt lgkmcnt(0)
	s_branch .LBB0_85
